# speedup vs baseline: 1.0081x; 1.0081x over previous
; #define MFMA(a, b, c) __builtin_amdgcn_mfma_f32_16x16x32_bf16((a), (b), (c), 0, 0, 0)
; #define ADV() { ga += 32; gb += 32; ck += 32; if (ck == K) { ck = 0; citem += gridDim.x; const int ci_ = citem < total ? citem : total - 1; SETPTR(ci_) } }
; #define WAITSTEP() { if (a2) WAITV(4); else WAITV(3); }
;     ...
;     for (int kt = 0; kt < nk; ++kt) {
;       if (VAR != 1) { const char* base = lds + scur; bf16x8 a[MI], b[4];
; #pragma unroll
;         for (int i = 0; i < 4; ++i) b[i] = *(const bf16x8*)(base + boff + i * 1024);
; #pragma unroll
;         for (int i = 0; i < MI; ++i) a[i] = *(const bf16x8*)(base + aoff + i * 1024);
; #pragma unroll
;         for (int i = 0; i < MI; ++i)
; #pragma unroll
;           for (int j = 0; j < 4; ++j) acc[i][j] = MFMA(a[i], b[j], acc[i][j]);
;         if (VAR != 2) GLDS(snext)
;     ...
;         if (MI == 8) {
;           __builtin_amdgcn_sched_group_barrier(0x100, MI + 4, 0);
; #pragma unroll
;           for (int g = 0; g < 4; ++g) { __builtin_amdgcn_sched_group_barrier(0x008, 7, 0); __builtin_amdgcn_sched_group_barrier(0x010, 1, 0); }
;           __builtin_amdgcn_sched_group_barrier(0x008, 4, 0);
;         } else if (MI == 6) {
;           __builtin_amdgcn_sched_group_barrier(0x100, MI + 4, 0);
; #pragma unroll
;           for (int g = 0; g < 4; ++g) { __builtin_amdgcn_sched_group_barrier(0x008, 5, 0); __builtin_amdgcn_sched_group_barrier(0x010, 1, 0); }
;           __builtin_amdgcn_sched_group_barrier(0x008, 4, 0);
;         }
;     ...
;       }
;       ADV()
;       if (VAR == 2) {} else WAITSTEP()
;       __builtin_amdgcn_s_barrier();
.Lffn8_hi:
	s_add_i32 s62, s4, 0
	v_add3_u32 v140, s62, v143, v144
	v_add3_u32 v128, s62, v145, v144
	ds_read_b128 v[158:161], v140
	ds_read_b128 v[146:149], v128 offset:16384
	ds_read_b128 v[150:153], v128 offset:17408
	ds_read_b128 v[154:157], v128 offset:18432
	ds_read_b128 v[162:165], v128 offset:19456
	ds_read_b128 v[166:169], v140 offset:1024
	ds_read_b128 v[170:173], v140 offset:2048
	ds_read_b128 v[174:177], v140 offset:3072
	ds_read_b128 v[178:181], v140 offset:4096
	ds_read_b128 v[182:185], v140 offset:5120
	ds_read_b128 v[186:189], v140 offset:6144
	ds_read_b128 v[190:193], v140 offset:7168
	s_waitcnt lgkmcnt(10)
	v_mfma_f32_16x16x32_bf16 v[124:127], v[158:161], v[146:149], v[124:127]
	s_waitcnt lgkmcnt(9)
	v_mfma_f32_16x16x32_bf16 v[120:123], v[158:161], v[150:153], v[120:123]
	s_add_i32 s62, s5, s100
	s_mov_b32 m0, s62
	v_lshl_add_u64 v[194:195], v[136:137], 0, s[50:51]
	v_lshl_add_u64 v[196:197], v[138:139], 0, s[50:51]
	v_lshl_add_u64 v[244:245], v[136:137], 0, 64
	v_lshl_add_u64 v[246:247], v[194:195], 0, 64
	v_lshl_add_u64 v[248:249], v[138:139], 0, 64
	v_lshl_add_u64 v[250:251], v[196:197], 0, 64
	s_waitcnt lgkmcnt(8)
	v_mfma_f32_16x16x32_bf16 v[116:119], v[158:161], v[154:157], v[116:119]
	s_waitcnt lgkmcnt(7)
	v_mfma_f32_16x16x32_bf16 v[112:115], v[158:161], v[162:165], v[112:115]
	global_load_lds_dwordx4 v[136:137], off
	s_add_i32 m0, s62, 0x2000
	ds_read_b128 v[228:231], v128 offset:49152
	ds_read_b128 v[232:235], v128 offset:50176
	ds_read_b128 v[236:239], v128 offset:51200
	ds_read_b128 v[240:243], v128 offset:52224
	ds_read_b128 v[158:161], v140 offset:32768
	s_waitcnt lgkmcnt(11)
	v_mfma_f32_16x16x32_bf16 v[108:111], v[166:169], v[146:149], v[108:111]
	v_mfma_f32_16x16x32_bf16 v[104:107], v[166:169], v[150:153], v[104:107]
	v_mfma_f32_16x16x32_bf16 v[100:103], v[166:169], v[154:157], v[100:103]
	global_load_lds_dwordx4 v[194:195], off
	s_add_i32 m0, s62, 0x4000
	v_mfma_f32_16x16x32_bf16 v[96:99], v[166:169], v[162:165], v[96:99]
	ds_read_b128 v[166:169], v140 offset:33792
	s_waitcnt lgkmcnt(11)
	v_mfma_f32_16x16x32_bf16 v[92:95], v[170:173], v[146:149], v[92:95]
	v_mfma_f32_16x16x32_bf16 v[88:91], v[170:173], v[150:153], v[88:91]
	global_load_lds_dwordx4 v[138:139], off
	s_add_i32 m0, s62, 0x6000
	v_mfma_f32_16x16x32_bf16 v[84:87], v[170:173], v[154:157], v[84:87]
	v_mfma_f32_16x16x32_bf16 v[80:83], v[170:173], v[162:165], v[80:83]
	ds_read_b128 v[170:173], v140 offset:34816
	s_waitcnt lgkmcnt(11)
	v_mfma_f32_16x16x32_bf16 v[76:79], v[174:177], v[146:149], v[76:79]
	global_load_lds_dwordx4 v[196:197], off
	s_add_i32 m0, s62, 0x8000
	v_mfma_f32_16x16x32_bf16 v[72:75], v[174:177], v[150:153], v[72:75]
	v_mfma_f32_16x16x32_bf16 v[68:71], v[174:177], v[154:157], v[68:71]
	v_mfma_f32_16x16x32_bf16 v[64:67], v[174:177], v[162:165], v[64:67]
	global_load_lds_dwordx4 v[244:245], off
	s_add_i32 m0, s62, 0xa000
	ds_read_b128 v[174:177], v140 offset:35840
	s_waitcnt lgkmcnt(11)
	v_mfma_f32_16x16x32_bf16 v[60:63], v[178:181], v[146:149], v[60:63]
	v_mfma_f32_16x16x32_bf16 v[56:59], v[178:181], v[150:153], v[56:59]
	v_mfma_f32_16x16x32_bf16 v[52:55], v[178:181], v[154:157], v[52:55]
	global_load_lds_dwordx4 v[246:247], off
	s_add_i32 m0, s62, 0xc000
	v_mfma_f32_16x16x32_bf16 v[48:51], v[178:181], v[162:165], v[48:51]
	ds_read_b128 v[178:181], v140 offset:36864
	s_waitcnt lgkmcnt(11)
	v_mfma_f32_16x16x32_bf16 v[40:43], v[182:185], v[146:149], v[40:43]
	v_mfma_f32_16x16x32_bf16 v[44:47], v[182:185], v[150:153], v[44:47]
	global_load_lds_dwordx4 v[248:249], off
	s_add_i32 m0, s62, 0xe000
	v_mfma_f32_16x16x32_bf16 v[32:35], v[182:185], v[154:157], v[32:35]
	v_mfma_f32_16x16x32_bf16 v[36:39], v[182:185], v[162:165], v[36:39]
	ds_read_b128 v[182:185], v140 offset:37888
	s_waitcnt lgkmcnt(11)
	v_mfma_f32_16x16x32_bf16 v[24:27], v[186:189], v[146:149], v[24:27]
	global_load_lds_dwordx4 v[250:251], off
	v_mfma_f32_16x16x32_bf16 v[28:31], v[186:189], v[150:153], v[28:31]
	v_mfma_f32_16x16x32_bf16 v[16:19], v[186:189], v[154:157], v[16:19]
	v_mfma_f32_16x16x32_bf16 v[20:23], v[186:189], v[162:165], v[20:23]
	ds_read_b128 v[186:189], v140 offset:38912
	s_waitcnt lgkmcnt(11)
	v_mfma_f32_16x16x32_bf16 v[8:11], v[190:193], v[146:149], v[8:11]
	v_mfma_f32_16x16x32_bf16 v[12:15], v[190:193], v[150:153], v[12:15]
	v_mfma_f32_16x16x32_bf16 v[0:3], v[190:193], v[154:157], v[0:3]
	v_mfma_f32_16x16x32_bf16 v[4:7], v[190:193], v[162:165], v[4:7]
	ds_read_b128 v[190:193], v140 offset:39936
	s_waitcnt lgkmcnt(7)
	v_mfma_f32_16x16x32_bf16 v[124:127], v[158:161], v[228:231], v[124:127]
	v_mfma_f32_16x16x32_bf16 v[120:123], v[158:161], v[232:235], v[120:123]
	v_mfma_f32_16x16x32_bf16 v[116:119], v[158:161], v[236:239], v[116:119]
	v_mfma_f32_16x16x32_bf16 v[112:115], v[158:161], v[240:243], v[112:115]
	s_waitcnt lgkmcnt(6)
	v_mfma_f32_16x16x32_bf16 v[108:111], v[166:169], v[228:231], v[108:111]
	v_mfma_f32_16x16x32_bf16 v[104:107], v[166:169], v[232:235], v[104:107]
	v_mfma_f32_16x16x32_bf16 v[100:103], v[166:169], v[236:239], v[100:103]
	v_mfma_f32_16x16x32_bf16 v[96:99], v[166:169], v[240:243], v[96:99]
	s_waitcnt lgkmcnt(5)
	v_mfma_f32_16x16x32_bf16 v[92:95], v[170:173], v[228:231], v[92:95]
	v_mfma_f32_16x16x32_bf16 v[88:91], v[170:173], v[232:235], v[88:91]
	v_mfma_f32_16x16x32_bf16 v[84:87], v[170:173], v[236:239], v[84:87]
	v_mfma_f32_16x16x32_bf16 v[80:83], v[170:173], v[240:243], v[80:83]
	s_waitcnt lgkmcnt(4)
	v_mfma_f32_16x16x32_bf16 v[76:79], v[174:177], v[228:231], v[76:79]
	v_mfma_f32_16x16x32_bf16 v[72:75], v[174:177], v[232:235], v[72:75]
	v_mfma_f32_16x16x32_bf16 v[68:71], v[174:177], v[236:239], v[68:71]
	v_mfma_f32_16x16x32_bf16 v[64:67], v[174:177], v[240:243], v[64:67]
	s_waitcnt lgkmcnt(3)
	v_mfma_f32_16x16x32_bf16 v[60:63], v[178:181], v[228:231], v[60:63]
	v_mfma_f32_16x16x32_bf16 v[56:59], v[178:181], v[232:235], v[56:59]
	v_mfma_f32_16x16x32_bf16 v[52:55], v[178:181], v[236:239], v[52:55]
	v_mfma_f32_16x16x32_bf16 v[48:51], v[178:181], v[240:243], v[48:51]
	s_waitcnt lgkmcnt(2)
	v_mfma_f32_16x16x32_bf16 v[40:43], v[182:185], v[228:231], v[40:43]
	v_mfma_f32_16x16x32_bf16 v[44:47], v[182:185], v[232:235], v[44:47]
	v_mfma_f32_16x16x32_bf16 v[32:35], v[182:185], v[236:239], v[32:35]
	v_mfma_f32_16x16x32_bf16 v[36:39], v[182:185], v[240:243], v[36:39]
	s_waitcnt lgkmcnt(1)
	v_mfma_f32_16x16x32_bf16 v[24:27], v[186:189], v[228:231], v[24:27]
	v_mfma_f32_16x16x32_bf16 v[28:31], v[186:189], v[232:235], v[28:31]
	v_mfma_f32_16x16x32_bf16 v[16:19], v[186:189], v[236:239], v[16:19]
	v_mfma_f32_16x16x32_bf16 v[20:23], v[186:189], v[240:243], v[20:23]
	s_waitcnt lgkmcnt(0)
	v_mfma_f32_16x16x32_bf16 v[8:11], v[190:193], v[228:231], v[8:11]
	v_mfma_f32_16x16x32_bf16 v[12:15], v[190:193], v[232:235], v[12:15]
	v_mfma_f32_16x16x32_bf16 v[0:3], v[190:193], v[236:239], v[0:3]
	v_mfma_f32_16x16x32_bf16 v[4:7], v[190:193], v[240:243], v[4:7]
	s_add_i32 s8, s8, 64
	s_cmpk_lg_i32 s8, 0x400
	s_cbranch_scc0 .LBB0_208
